# input-LN and modulate passes rewritten the same way (hoisted gamma/beta, next-row prefetch); gdn kk loop double-buffered over two register sets
# speedup vs baseline: 1.0715x; 1.0162x over previous
; DI float lo16(unsigned w) { return __uint_as_float(w << 16); }
; DI float hi16(unsigned w) { return __uint_as_float(w & 0xffff0000u); }
; DI void ln_pass(CP c, int mode, const float* gam, const float* bet, const float* modsc, const float* modsh, int bid, int nb, bool fin) {
;     ...
;     for (int r = bid * 8 + wave; r < MT; r += nb * 8) {
;         f32x4 v[4];
;         if (mode == 0) { const float* src = r < MP ? c->in[I_XP] + (size_t)r * DM : c->in[I_XS] + (size_t)(r - MP) * DM;
; #pragma unroll
;             for (int i = 0; i < 4; ++i) v[i] = *(const f32x4*)(src + lane * 4 + 256 * i); }
;         else {
; #pragma unroll
;             for (int i = 0; i < 4; ++i) { const u32x2 w = *(const u32x2*)(XB + (size_t)r * DM + lane * 4 + 256 * i); v[i] = (f32x4){lo16(w.x), hi16(w.x), lo16(w.y), hi16(w.y)}; } }
; __global__ void __launch_bounds__(512) fwd_megakernel(Ctx carg) {
;     ...
;         else if (ph == 1) { const int skip = (nb > 96) ? 48 : 0;
;             if (bid >= skip) ln_pass(c, 0, c->in[I_LN0G], c->in[I_LN0B], nullptr, nullptr, bid - skip, nb - skip, false); }
;         else if (ph == 2) { ln_pass(c, 1, nullptr, nullptr, MOD + 1024, MOD, bid, nb, false); }
.Lmini_done:
	v_readlane_b32 s6, v254, 28
	v_readlane_b32 s76, v254, 24
	v_readlane_b32 s7, v254, 29
	v_readlane_b32 s77, v254, 25
	v_readlane_b32 s88, v254, 26
	s_mov_b64 s[8:9], -1
	s_mov_b64 s[0:1], 0
	s_cmp_lt_i32 s6, 1
	s_mov_b64 s[6:7], 0
	v_readlane_b32 s89, v254, 27
	s_movk_i32 s81, 0x41ff
	s_movk_i32 s77, 0x300
	s_cbranch_scc1 .LBB0_172
	v_readlane_b32 s6, v254, 28
	s_cmp_gt_i32 s6, 1
	v_readlane_b32 s7, v254, 29
	s_cbranch_scc0 .LBB0_174
	s_cmp_eq_u32 s6, 2
	s_mov_b64 s[6:7], -1
	s_cbranch_scc0 .LBB0_171
	s_waitcnt vmcnt(0)
	v_mov_b32_e32 v9, v188
	v_readlane_b32 s6, v252, 39
	v_ashrrev_i32_e32 v6, 6, v9
	v_readlane_b32 s7, v252, 40
	v_add_u32_e32 v8, s6, v6
	s_movk_i32 s6, 0x4200
	v_cmp_gt_i32_e32 vcc, s6, v8
	s_and_saveexec_b64 s[6:7], vcc
	s_cbranch_execz .LBB0_170
	v_lshlrev_b32_e32 v0, 4, v9
	v_and_b32_e32 v0, 0x3f0, v0
	v_lshl_add_u64 v[2:3], s[20:21], 0, v[0:1]
	s_mov_b64 s[8:9], 0x5000
	v_lshl_add_u64 v[2:3], v[2:3], 0, s[8:9]
	v_readlane_b32 s8, v254, 34
	v_readlane_b32 s9, v254, 35
	v_ashrrev_i32_e32 v7, 31, v6
	s_nop 0
	v_lshl_add_u64 v[4:5], s[8:9], 0, v[0:1]
	v_readlane_b32 s8, v252, 39
	v_readlane_b32 s9, v252, 40
	v_and_b32_e32 v0, 63, v9
	s_nop 0
	v_lshl_add_u64 v[6:7], s[8:9], 0, v[6:7]
	v_lshlrev_b64 v[6:7], 11, v[6:7]
	v_lshl_or_b32 v6, v0, 3, v6
	v_lshl_add_u64 v[6:7], s[20:21], 0, v[6:7]
	s_mov_b64 s[8:9], 0x123c4000
	v_lshl_add_u64 v[6:7], v[6:7], 0, s[8:9]
	s_mov_b64 s[8:9], 0
	v_add_co_u32_e32 v18, vcc, 0xa342000, v6
	s_nop 1
	v_addc_co_u32_e32 v19, vcc, 0, v7, vcc
	global_load_dwordx2 v[92:93], v[18:19], off
	global_load_dwordx2 v[94:95], v[18:19], off offset:512
	global_load_dwordx2 v[96:97], v[18:19], off offset:1024
	global_load_dwordx2 v[98:99], v[18:19], off offset:1536
; DI unsigned pk2(float lo, float hi) { const hwf2_t v = {lo, hi}; const hwbf2_t b = __builtin_convertvector(v, hwbf2_t); return __builtin_bit_cast(unsigned, b); }
; DI float lo16(unsigned w) { return __uint_as_float(w << 16); }
; DI float hi16(unsigned w) { return __uint_as_float(w & 0xffff0000u); }
; DI void ln_pass(CP c, int mode, const float* gam, const float* bet, const float* modsc, const float* modsh, int bid, int nb, bool fin) {
;     ...
;     for (int r = bid * 8 + wave; r < MT; r += nb * 8) {
;         f32x4 v[4];
;         if (mode == 0) { const float* src = r < MP ? c->in[I_XP] + (size_t)r * DM : c->in[I_XS] + (size_t)(r - MP) * DM;
; #pragma unroll
;             for (int i = 0; i < 4; ++i) v[i] = *(const f32x4*)(src + lane * 4 + 256 * i); }
;         else {
; #pragma unroll
;             for (int i = 0; i < 4; ++i) { const u32x2 w = *(const u32x2*)(XB + (size_t)r * DM + lane * 4 + 256 * i); v[i] = (f32x4){lo16(w.x), hi16(w.x), lo16(w.y), hi16(w.y)}; } }
;         if (mode != 1) {
;             float s = 0.f;
; #pragma unroll
;             for (int i = 0; i < 4; ++i) s += v[i][0] + v[i][1] + v[i][2] + v[i][3];
;             const float mean = wave_sum(s) * (1.f / 1024.f); float q = 0.f;
; #pragma unroll
;             for (int i = 0; i < 4; ++i) { const f32x4 d = v[i] - mean; q += d[0] * d[0] + d[1] * d[1] + d[2] * d[2] + d[3] * d[3]; }
;             const float rstd = rsqrtf(wave_sum(q) * (1.f / 1024.f) + 1e-5f);
; #pragma unroll
;             for (int i = 0; i < 4; ++i) { const int col = lane * 4 + 256 * i; const f32x4 g = *(const f32x4*)(gam + col), b = *(const f32x4*)(bet + col);
;                 v[i] = (v[i] - mean) * rstd * g + b;
;                 if (fin) *(f32x4*)(c->out + (size_t)r * DM + col) = v[i];
;                 else { u32x2 w; w.x = pk2(v[i][0], v[i][1]); w.y = pk2(v[i][2], v[i][3]); *(u32x2*)(XB + (size_t)r * DM + col) = w; } }
;         }
;         if (modsc) { const int mr = modrow_of(r);
; #pragma unroll
;             for (int i = 0; i < 4; ++i) { const int col = lane * 4 + 256 * i; const f32x4 sc = *(const f32x4*)(modsc + (size_t)mr * 12288 + col), sh = *(const f32x4*)(modsh + (size_t)mr * 12288 + col);
;                 const f32x4 h = v[i] * (sc + 1.0f) + sh; u32x2 w; w.x = pk2(h[0], h[1]); w.y = pk2(h[2], h[3]);
;                 *(u32x2*)(H + (size_t)r * DM + col) = w; } }
.LBB0_169:
	v_add_u32_e32 v0, 0xffffc000, v8
	v_lshrrev_b32_e32 v0, 4, v0
	v_add_u32_e32 v0, 1, v0
	v_cmp_lt_i32_e32 vcc, s3, v8
	s_nop 1
	v_cndmask_b32_e32 v0, 0, v0, vcc
	v_mad_u64_u32 v[22:23], s[12:13], v0, s86, v[2:3]
	v_mad_u64_u32 v[24:25], s[12:13], v0, s86, v[4:5]
	global_load_dwordx4 v[108:111], v[22:23], off
	global_load_dwordx4 v[112:115], v[22:23], off offset:1024
	global_load_dwordx4 v[116:119], v[22:23], off offset:2048
	global_load_dwordx4 v[120:123], v[22:23], off offset:3072
	global_load_dwordx4 v[124:127], v[24:25], off
	global_load_dwordx4 v[128:131], v[24:25], off offset:1024
	global_load_dwordx4 v[132:135], v[24:25], off offset:2048
	global_load_dwordx4 v[136:139], v[24:25], off offset:3072
	s_waitcnt vmcnt(8)
	v_lshl_add_u64 v[48:49], v[18:19], 0, s[44:45]
	global_load_dwordx2 v[100:101], v[48:49], off
	global_load_dwordx2 v[102:103], v[48:49], off offset:512
	global_load_dwordx2 v[104:105], v[48:49], off offset:1024
	global_load_dwordx2 v[106:107], v[48:49], off offset:1536
	v_lshlrev_b32_e32 v140, 16, v92
	v_and_b32_e32 v141, 0xffff0000, v92
	v_lshlrev_b32_e32 v142, 16, v93
	v_and_b32_e32 v143, 0xffff0000, v93
	v_lshlrev_b32_e32 v144, 16, v94
	v_and_b32_e32 v145, 0xffff0000, v94
	v_lshlrev_b32_e32 v146, 16, v95
	v_and_b32_e32 v147, 0xffff0000, v95
	v_lshlrev_b32_e32 v148, 16, v96
	v_and_b32_e32 v149, 0xffff0000, v96
	v_lshlrev_b32_e32 v150, 16, v97
	v_and_b32_e32 v151, 0xffff0000, v97
	v_lshlrev_b32_e32 v152, 16, v98
	v_and_b32_e32 v153, 0xffff0000, v98
	v_lshlrev_b32_e32 v154, 16, v99
	v_and_b32_e32 v155, 0xffff0000, v99
	s_waitcnt vmcnt(4)
	v_add_f32_e32 v108, 1.0, v108
	v_add_f32_e32 v109, 1.0, v109
	v_add_f32_e32 v110, 1.0, v110
	v_add_f32_e32 v111, 1.0, v111
	v_add_f32_e32 v112, 1.0, v112
	v_add_f32_e32 v113, 1.0, v113
	v_add_f32_e32 v114, 1.0, v114
	v_add_f32_e32 v115, 1.0, v115
	v_add_f32_e32 v116, 1.0, v116
	v_add_f32_e32 v117, 1.0, v117
	v_add_f32_e32 v118, 1.0, v118
	v_add_f32_e32 v119, 1.0, v119
	v_add_f32_e32 v120, 1.0, v120
	v_add_f32_e32 v121, 1.0, v121
	v_add_f32_e32 v122, 1.0, v122
	v_add_f32_e32 v123, 1.0, v123
	v_fma_f32 v108, v108, v140, v124
	v_fma_f32 v109, v109, v141, v125
	v_fma_f32 v110, v110, v142, v126
	v_fma_f32 v111, v111, v143, v127
	v_fma_f32 v112, v112, v144, v128
	v_fma_f32 v113, v113, v145, v129
	v_fma_f32 v114, v114, v146, v130
	v_fma_f32 v115, v115, v147, v131
	v_fma_f32 v116, v116, v148, v132
	v_fma_f32 v117, v117, v149, v133
	v_fma_f32 v118, v118, v150, v134
	v_fma_f32 v119, v119, v151, v135
	v_fma_f32 v120, v120, v152, v136
	v_fma_f32 v121, v121, v153, v137
	v_fma_f32 v122, v122, v154, v138
	v_fma_f32 v123, v123, v155, v139
	v_cvt_pk_bf16_f32 v50, v108, v109
	v_cvt_pk_bf16_f32 v51, v110, v111
	global_store_dwordx2 v[6:7], v[50:51], off
	v_cvt_pk_bf16_f32 v52, v112, v113
	v_cvt_pk_bf16_f32 v53, v114, v115
	global_store_dwordx2 v[6:7], v[52:53], off offset:512
	v_cvt_pk_bf16_f32 v54, v116, v117
	v_cvt_pk_bf16_f32 v55, v118, v119
	global_store_dwordx2 v[6:7], v[54:55], off offset:1024
	v_cvt_pk_bf16_f32 v56, v120, v121
	v_cvt_pk_bf16_f32 v57, v122, v123
	global_store_dwordx2 v[6:7], v[56:57], off offset:1536
	v_add_u32_e32 v8, s76, v8
	v_mov_b32_e32 v18, v48
	v_mov_b32_e32 v19, v49
	v_lshl_add_u64 v[6:7], v[6:7], 0, s[44:45]
	v_cmp_lt_i32_e32 vcc, s81, v8
	s_or_b64 s[8:9], vcc, s[8:9]
	s_andn2_b64 exec, exec, s[8:9]
	s_cbranch_execz .LBB0_170
	v_add_u32_e32 v0, 0xffffc000, v8
	v_lshrrev_b32_e32 v0, 4, v0
	v_add_u32_e32 v0, 1, v0
	v_cmp_lt_i32_e32 vcc, s3, v8
	s_nop 1
	v_cndmask_b32_e32 v0, 0, v0, vcc
	v_mad_u64_u32 v[22:23], s[12:13], v0, s86, v[2:3]
	v_mad_u64_u32 v[24:25], s[12:13], v0, s86, v[4:5]
	global_load_dwordx4 v[108:111], v[22:23], off
	global_load_dwordx4 v[112:115], v[22:23], off offset:1024
	global_load_dwordx4 v[116:119], v[22:23], off offset:2048
	global_load_dwordx4 v[120:123], v[22:23], off offset:3072
	global_load_dwordx4 v[124:127], v[24:25], off
	global_load_dwordx4 v[128:131], v[24:25], off offset:1024
	global_load_dwordx4 v[132:135], v[24:25], off offset:2048
	global_load_dwordx4 v[136:139], v[24:25], off offset:3072
	s_waitcnt vmcnt(8)
	v_lshl_add_u64 v[48:49], v[18:19], 0, s[44:45]
	global_load_dwordx2 v[92:93], v[48:49], off
	global_load_dwordx2 v[94:95], v[48:49], off offset:512
	global_load_dwordx2 v[96:97], v[48:49], off offset:1024
	global_load_dwordx2 v[98:99], v[48:49], off offset:1536
	v_lshlrev_b32_e32 v140, 16, v100
	v_and_b32_e32 v141, 0xffff0000, v100
	v_lshlrev_b32_e32 v142, 16, v101
	v_and_b32_e32 v143, 0xffff0000, v101
	v_lshlrev_b32_e32 v144, 16, v102
	v_and_b32_e32 v145, 0xffff0000, v102
	v_lshlrev_b32_e32 v146, 16, v103
	v_and_b32_e32 v147, 0xffff0000, v103
	v_lshlrev_b32_e32 v148, 16, v104
	v_and_b32_e32 v149, 0xffff0000, v104
	v_lshlrev_b32_e32 v150, 16, v105
	v_and_b32_e32 v151, 0xffff0000, v105
	v_lshlrev_b32_e32 v152, 16, v106
	v_and_b32_e32 v153, 0xffff0000, v106
	v_lshlrev_b32_e32 v154, 16, v107
	v_and_b32_e32 v155, 0xffff0000, v107
	s_waitcnt vmcnt(4)
	v_add_f32_e32 v108, 1.0, v108
	v_add_f32_e32 v109, 1.0, v109
	v_add_f32_e32 v110, 1.0, v110
	v_add_f32_e32 v111, 1.0, v111
	v_add_f32_e32 v112, 1.0, v112
	v_add_f32_e32 v113, 1.0, v113
	v_add_f32_e32 v114, 1.0, v114
	v_add_f32_e32 v115, 1.0, v115
	v_add_f32_e32 v116, 1.0, v116
	v_add_f32_e32 v117, 1.0, v117
	v_add_f32_e32 v118, 1.0, v118
	v_add_f32_e32 v119, 1.0, v119
	v_add_f32_e32 v120, 1.0, v120
	v_add_f32_e32 v121, 1.0, v121
	v_add_f32_e32 v122, 1.0, v122
	v_add_f32_e32 v123, 1.0, v123
	v_fma_f32 v108, v108, v140, v124
	v_fma_f32 v109, v109, v141, v125
	v_fma_f32 v110, v110, v142, v126
	v_fma_f32 v111, v111, v143, v127
	v_fma_f32 v112, v112, v144, v128
	v_fma_f32 v113, v113, v145, v129
	v_fma_f32 v114, v114, v146, v130
	v_fma_f32 v115, v115, v147, v131
	v_fma_f32 v116, v116, v148, v132
	v_fma_f32 v117, v117, v149, v133
	v_fma_f32 v118, v118, v150, v134
	v_fma_f32 v119, v119, v151, v135
	v_fma_f32 v120, v120, v152, v136
	v_fma_f32 v121, v121, v153, v137
	v_fma_f32 v122, v122, v154, v138
	v_fma_f32 v123, v123, v155, v139
	v_cvt_pk_bf16_f32 v50, v108, v109
	v_cvt_pk_bf16_f32 v51, v110, v111
	global_store_dwordx2 v[6:7], v[50:51], off
	v_cvt_pk_bf16_f32 v52, v112, v113
	v_cvt_pk_bf16_f32 v53, v114, v115
	global_store_dwordx2 v[6:7], v[52:53], off offset:512
	v_cvt_pk_bf16_f32 v54, v116, v117
	v_cvt_pk_bf16_f32 v55, v118, v119
	global_store_dwordx2 v[6:7], v[54:55], off offset:1024
	v_cvt_pk_bf16_f32 v56, v120, v121
	v_cvt_pk_bf16_f32 v57, v122, v123
	global_store_dwordx2 v[6:7], v[56:57], off offset:1536
	v_add_u32_e32 v8, s76, v8
	v_mov_b32_e32 v18, v48
	v_mov_b32_e32 v19, v49
	v_lshl_add_u64 v[6:7], v[6:7], 0, s[44:45]
	v_cmp_lt_i32_e32 vcc, s81, v8
	s_or_b64 s[8:9], vcc, s[8:9]
	s_andn2_b64 exec, exec, s[8:9]
	s_cbranch_execnz .LBB0_169

; DI float lo16(unsigned w) { return __uint_as_float(w << 16); }
; DI float hi16(unsigned w) { return __uint_as_float(w & 0xffff0000u); }
; DI float wave_sum(float v) { for (int o = 32; o >= 1; o >>= 1) v += __shfl_xor(v, o); return v; }
; DI int get_tid() { int t = (int)threadIdx.x; asm volatile("" : "+v"(t)); return t; }
; DI void ln_pass(CP c, int mode, const float* gam, const float* bet, const float* modsc, const float* modsh, int bid, int nb, bool fin) {
;     const int tid = get_tid(), lane = tid & 63, wave = tid >> 6;
;     bf16_t* XB = (bf16_t*)(c->ws + WS_XB); bf16_t* H = (bf16_t*)(c->ws + WS_H);
;     for (int r = bid * 8 + wave; r < MT; r += nb * 8) {
;         f32x4 v[4];
;         if (mode == 0) { const float* src = r < MP ? c->in[I_XP] + (size_t)r * DM : c->in[I_XS] + (size_t)(r - MP) * DM;
; #pragma unroll
;             for (int i = 0; i < 4; ++i) v[i] = *(const f32x4*)(src + lane * 4 + 256 * i); }
;         else {
; #pragma unroll
;             for (int i = 0; i < 4; ++i) { const u32x2 w = *(const u32x2*)(XB + (size_t)r * DM + lane * 4 + 256 * i); v[i] = (f32x4){lo16(w.x), hi16(w.x), lo16(w.y), hi16(w.y)}; } }
;         if (mode != 1) {
;             float s = 0.f;
; #pragma unroll
;             for (int i = 0; i < 4; ++i) s += v[i][0] + v[i][1] + v[i][2] + v[i][3];
;             const float mean = wave_sum(s) * (1.f / 1024.f); float q = 0.f;
; #pragma unroll
;             for (int i = 0; i < 4; ++i) { const f32x4 d = v[i] - mean; q += d[0] * d[0] + d[1] * d[1] + d[2] * d[2] + d[3] * d[3]; }
;             const float rstd = rsqrtf(wave_sum(q) * (1.f / 1024.f) + 1e-5f);
.LBB0_174:
	s_mov_b64 s[6:7], 0
	s_and_b64 vcc, exec, s[8:9]
	s_cbranch_vccz .LBB0_180
	v_readlane_b32 s8, v249, 4
	v_readlane_b32 s9, v249, 5
	s_andn2_b64 vcc, exec, s[8:9]
	s_cbranch_vccnz .LBB0_180
	s_waitcnt vmcnt(0)
	v_mov_b32_e32 v2, v188
	v_readlane_b32 s8, v249, 6
	v_ashrrev_i32_e32 v0, 6, v2
	s_nop 0
	v_add_u32_e32 v24, s8, v0
	s_movk_i32 s8, 0x4200
	v_cmp_gt_i32_e32 vcc, s8, v24
	s_and_saveexec_b64 s[8:9], vcc
	s_movk_i32 s14, 0x4000
	s_mov_b32 s22, 0x800000
	s_cbranch_execz .LBB0_179
	s_load_dwordx4 s[16:19], s[46:47], 0x50
	v_lshlrev_b32_e32 v0, 2, v2
	v_and_b32_e32 v4, 0xfc, v0
	v_lshlrev_b32_e32 v0, 2, v4
	v_xor_b32_e32 v3, 32, v196
	s_waitcnt lgkmcnt(0)
	v_lshl_add_u64 v[26:27], s[16:17], 0, v[0:1]
	v_lshl_add_u64 v[28:29], s[18:19], 0, v[0:1]
	v_and_b32_e32 v0, 64, v196
	v_add_u32_e32 v0, 64, v0
	v_cmp_lt_i32_e32 vcc, v3, v0
	v_ashrrev_i32_e32 v25, 31, v24
	v_lshlrev_b64 v[6:7], 11, v[24:25]
	v_cndmask_b32_e32 v3, v196, v3, vcc
	v_lshlrev_b32_e32 v36, 2, v3
	v_xor_b32_e32 v3, 16, v196
	v_cmp_lt_i32_e32 vcc, v3, v0
	s_mov_b64 s[12:13], 0x1c706000
	v_lshlrev_b32_e32 v32, 2, v4
	v_cndmask_b32_e32 v3, v196, v3, vcc
	v_lshlrev_b32_e32 v37, 2, v3
	v_xor_b32_e32 v3, 8, v196
	v_cmp_lt_i32_e32 vcc, v3, v0
	s_nop 1
	v_cndmask_b32_e32 v3, v196, v3, vcc
	v_lshlrev_b32_e32 v38, 2, v3
	v_xor_b32_e32 v3, 4, v196
	v_cmp_lt_i32_e32 vcc, v3, v0
	s_nop 1
	v_cndmask_b32_e32 v3, v196, v3, vcc
	v_lshlrev_b32_e32 v39, 2, v3
	v_xor_b32_e32 v3, 2, v196
	v_cmp_lt_i32_e32 vcc, v3, v0
	s_nop 1
	v_cndmask_b32_e32 v3, v196, v3, vcc
	v_lshlrev_b32_e32 v40, 2, v3
	v_xor_b32_e32 v3, 1, v196
	v_cmp_lt_i32_e32 vcc, v3, v0
	s_nop 1
	v_cndmask_b32_e32 v0, v196, v3, vcc
	v_lshlrev_b32_e32 v41, 2, v0
	v_and_b32_e32 v0, 63, v2
	v_lshl_or_b32 v6, v0, 3, v6
	v_lshl_add_u64 v[2:3], s[20:21], 0, v[6:7]
	v_lshl_add_u64 v[30:31], v[2:3], 0, s[12:13]
	s_mov_b64 s[12:13], 0
	s_load_dwordx2 s[98:99], s[46:47], 0x0
	s_load_dwordx2 s[100:101], s[46:47], 0x8
	global_load_dwordx4 v[60:63], v[26:27], off
	global_load_dwordx4 v[64:67], v[26:27], off offset:1024
	global_load_dwordx4 v[68:71], v[26:27], off offset:2048
	global_load_dwordx4 v[72:75], v[26:27], off offset:3072
	global_load_dwordx4 v[76:79], v[28:29], off
	global_load_dwordx4 v[80:83], v[28:29], off offset:1024
	global_load_dwordx4 v[84:87], v[28:29], off offset:2048
	global_load_dwordx4 v[88:91], v[28:29], off offset:3072
	v_mov_b32_e32 v33, v1
	s_waitcnt lgkmcnt(0)
	v_cmp_gt_i32_e32 vcc, s14, v24
	v_add_u32_e32 v0, 0xffffc000, v24
	v_mov_b32_e32 v4, s100
	v_mov_b32_e32 v5, s101
	v_mov_b32_e32 v6, s98
	v_mov_b32_e32 v7, s99
	v_cndmask_b32_e32 v2, v0, v24, vcc
	v_mov_b32_e32 v3, 0
	v_cndmask_b32_e32 v4, v4, v6, vcc
	v_cndmask_b32_e32 v5, v5, v7, vcc
	v_lshlrev_b64 v[2:3], 12, v[2:3]
	v_lshl_add_u64 v[2:3], v[4:5], 0, v[2:3]
	v_lshl_add_u64 v[2:3], v[2:3], 0, v[32:33]
	global_load_dwordx4 v[92:95], v[2:3], off
	global_load_dwordx4 v[96:99], v[2:3], off offset:1024
	global_load_dwordx4 v[100:103], v[2:3], off offset:2048
	global_load_dwordx4 v[104:107], v[2:3], off offset:3072
.LBB0_178:
	v_lshl_add_u64 v[24:25], v[24:25], 0, s[88:89]
	v_cmp_lt_i32_e32 vcc, s81, v24
	s_or_b64 s[12:13], vcc, s[12:13]
	s_cbranch_vccnz .Lln0_nopf_a
	v_cmp_gt_i32_e32 vcc, s14, v24
	v_add_u32_e32 v0, 0xffffc000, v24
	v_mov_b32_e32 v4, s100
	v_mov_b32_e32 v5, s101
	v_mov_b32_e32 v6, s98
	v_mov_b32_e32 v7, s99
	v_cndmask_b32_e32 v2, v0, v24, vcc
	v_mov_b32_e32 v3, 0
	v_cndmask_b32_e32 v4, v4, v6, vcc
	v_cndmask_b32_e32 v5, v5, v7, vcc
	v_lshlrev_b64 v[2:3], 12, v[2:3]
	v_lshl_add_u64 v[2:3], v[4:5], 0, v[2:3]
	v_lshl_add_u64 v[2:3], v[2:3], 0, v[32:33]
	global_load_dwordx4 v[108:111], v[2:3], off
	global_load_dwordx4 v[112:115], v[2:3], off offset:1024
	global_load_dwordx4 v[116:119], v[2:3], off offset:2048
	global_load_dwordx4 v[120:123], v[2:3], off offset:3072
.Lln0_nopf_a:
	s_waitcnt vmcnt(4)
	v_add_f32_e32 v0, v92, v93
	v_add_f32_e32 v0, v0, v94
	v_add_f32_e32 v0, v0, v95
	v_add_f32_e32 v0, v0, v96
	v_add_f32_e32 v0, v0, v97
	v_add_f32_e32 v0, v0, v98
	v_add_f32_e32 v0, v0, v99
	v_add_f32_e32 v0, v0, v100
	v_add_f32_e32 v0, v0, v101
	v_add_f32_e32 v0, v0, v102
	v_add_f32_e32 v0, v0, v103
	v_add_f32_e32 v0, v0, v104
	v_add_f32_e32 v0, v0, v105
	v_add_f32_e32 v0, v0, v106
	v_add_f32_e32 v0, v0, v107
	ds_bpermute_b32 v54, v36, v0
	s_waitcnt lgkmcnt(0)
	v_add_f32_e32 v0, v0, v54
	ds_bpermute_b32 v54, v37, v0
	s_waitcnt lgkmcnt(0)
	v_add_f32_e32 v0, v0, v54
	ds_bpermute_b32 v54, v38, v0
	s_waitcnt lgkmcnt(0)
	v_add_f32_e32 v0, v0, v54
	ds_bpermute_b32 v54, v39, v0
	s_waitcnt lgkmcnt(0)
	v_add_f32_e32 v0, v0, v54
	ds_bpermute_b32 v54, v40, v0
	s_waitcnt lgkmcnt(0)
	v_add_f32_e32 v0, v0, v54
	ds_bpermute_b32 v54, v41, v0
	s_waitcnt lgkmcnt(0)
	v_add_f32_e32 v0, v0, v54
	v_fmac_f32_e32 v92, 0xba800000, v0
	v_fmac_f32_e32 v93, 0xba800000, v0
	v_fmac_f32_e32 v94, 0xba800000, v0
	v_fmac_f32_e32 v95, 0xba800000, v0
	v_fmac_f32_e32 v96, 0xba800000, v0
	v_fmac_f32_e32 v97, 0xba800000, v0
	v_fmac_f32_e32 v98, 0xba800000, v0
	v_fmac_f32_e32 v99, 0xba800000, v0
	v_fmac_f32_e32 v100, 0xba800000, v0
	v_fmac_f32_e32 v101, 0xba800000, v0
	v_fmac_f32_e32 v102, 0xba800000, v0
	v_fmac_f32_e32 v103, 0xba800000, v0
	v_fmac_f32_e32 v104, 0xba800000, v0
	v_fmac_f32_e32 v105, 0xba800000, v0
	v_fmac_f32_e32 v106, 0xba800000, v0
	v_fmac_f32_e32 v107, 0xba800000, v0
	v_mul_f32_e32 v55, v92, v92
	v_fmac_f32_e32 v55, v93, v93
	v_fmac_f32_e32 v55, v94, v94
	v_fmac_f32_e32 v55, v95, v95
	v_fmac_f32_e32 v55, v96, v96
	v_fmac_f32_e32 v55, v97, v97
	v_fmac_f32_e32 v55, v98, v98
	v_fmac_f32_e32 v55, v99, v99
	v_fmac_f32_e32 v55, v100, v100
	v_fmac_f32_e32 v55, v101, v101
	v_fmac_f32_e32 v55, v102, v102
	v_fmac_f32_e32 v55, v103, v103
	v_fmac_f32_e32 v55, v104, v104
	v_fmac_f32_e32 v55, v105, v105
	v_fmac_f32_e32 v55, v106, v106
	v_fmac_f32_e32 v55, v107, v107
	ds_bpermute_b32 v54, v36, v55
	s_waitcnt lgkmcnt(0)
; DI unsigned pk2(float lo, float hi) { const hwf2_t v = {lo, hi}; const hwbf2_t b = __builtin_convertvector(v, hwbf2_t); return __builtin_bit_cast(unsigned, b); }
; DI float wave_sum(float v) { for (int o = 32; o >= 1; o >>= 1) v += __shfl_xor(v, o); return v; }
; DI void ln_pass(CP c, int mode, const float* gam, const float* bet, const float* modsc, const float* modsh, int bid, int nb, bool fin) {
;     ...
;             const float mean = wave_sum(s) * (1.f / 1024.f); float q = 0.f;
; #pragma unroll
;             for (int i = 0; i < 4; ++i) { const f32x4 d = v[i] - mean; q += d[0] * d[0] + d[1] * d[1] + d[2] * d[2] + d[3] * d[3]; }
;             const float rstd = rsqrtf(wave_sum(q) * (1.f / 1024.f) + 1e-5f);
; #pragma unroll
;             for (int i = 0; i < 4; ++i) { const int col = lane * 4 + 256 * i; const f32x4 g = *(const f32x4*)(gam + col), b = *(const f32x4*)(bet + col);
;                 v[i] = (v[i] - mean) * rstd * g + b;
;                 if (fin) *(f32x4*)(c->out + (size_t)r * DM + col) = v[i];
;                 else { u32x2 w; w.x = pk2(v[i][0], v[i][1]); w.y = pk2(v[i][2], v[i][3]); *(u32x2*)(XB + (size_t)r * DM + col) = w; } }
	v_add_f32_e32 v55, v55, v54
	ds_bpermute_b32 v54, v37, v55
	s_waitcnt lgkmcnt(0)
	v_add_f32_e32 v55, v55, v54
	ds_bpermute_b32 v54, v38, v55
	s_waitcnt lgkmcnt(0)
	v_add_f32_e32 v55, v55, v54
	ds_bpermute_b32 v54, v39, v55
	s_waitcnt lgkmcnt(0)
	v_add_f32_e32 v55, v55, v54
	ds_bpermute_b32 v54, v40, v55
	s_waitcnt lgkmcnt(0)
	v_add_f32_e32 v55, v55, v54
	ds_bpermute_b32 v54, v41, v55
	s_waitcnt lgkmcnt(0)
	v_add_f32_e32 v55, v55, v54
	v_fmamk_f32 v55, v55, 0x3a800000, v189
	v_rsq_f32_e32 v55, v55
	s_nop 0
	v_mul_f32_e32 v92, v92, v55
	v_mul_f32_e32 v93, v93, v55
	v_mul_f32_e32 v94, v94, v55
	v_mul_f32_e32 v95, v95, v55
	v_mul_f32_e32 v96, v96, v55
	v_mul_f32_e32 v97, v97, v55
	v_mul_f32_e32 v98, v98, v55
	v_mul_f32_e32 v99, v99, v55
	v_mul_f32_e32 v100, v100, v55
	v_mul_f32_e32 v101, v101, v55
	v_mul_f32_e32 v102, v102, v55
	v_mul_f32_e32 v103, v103, v55
	v_mul_f32_e32 v104, v104, v55
	v_mul_f32_e32 v105, v105, v55
	v_mul_f32_e32 v106, v106, v55
	v_mul_f32_e32 v107, v107, v55
	v_fma_f32 v92, v60, v92, v76
	v_fma_f32 v93, v61, v93, v77
	v_fma_f32 v94, v62, v94, v78
	v_fma_f32 v95, v63, v95, v79
	v_fma_f32 v96, v64, v96, v80
	v_fma_f32 v97, v65, v97, v81
	v_fma_f32 v98, v66, v98, v82
	v_fma_f32 v99, v67, v99, v83
	v_fma_f32 v100, v68, v100, v84
	v_fma_f32 v101, v69, v101, v85
	v_fma_f32 v102, v70, v102, v86
	v_fma_f32 v103, v71, v103, v87
	v_fma_f32 v104, v72, v104, v88
	v_fma_f32 v105, v73, v105, v89
	v_fma_f32 v106, v74, v106, v90
	v_fma_f32 v107, v75, v107, v91
	v_cvt_pk_bf16_f32 v16, v92, v93
	v_cvt_pk_bf16_f32 v17, v94, v95
	global_store_dwordx2 v[30:31], v[16:17], off
	v_cvt_pk_bf16_f32 v18, v96, v97
	v_cvt_pk_bf16_f32 v19, v98, v99
	global_store_dwordx2 v[30:31], v[18:19], off offset:512
	v_cvt_pk_bf16_f32 v20, v100, v101
	v_cvt_pk_bf16_f32 v21, v102, v103
	global_store_dwordx2 v[30:31], v[20:21], off offset:1024
	v_cvt_pk_bf16_f32 v22, v104, v105
	v_cvt_pk_bf16_f32 v23, v106, v107
	global_store_dwordx2 v[30:31], v[22:23], off offset:1536
	v_lshl_add_u64 v[30:31], v[30:31], 0, s[34:35]
	s_andn2_b64 exec, exec, s[12:13]
	s_cbranch_execz .LBB0_179
	v_lshl_add_u64 v[24:25], v[24:25], 0, s[88:89]
	v_cmp_lt_i32_e32 vcc, s81, v24
	s_or_b64 s[12:13], vcc, s[12:13]
	s_cbranch_vccnz .Lln0_nopf_b
	v_cmp_gt_i32_e32 vcc, s14, v24
	v_add_u32_e32 v0, 0xffffc000, v24
	v_mov_b32_e32 v4, s100
	v_mov_b32_e32 v5, s101
	v_mov_b32_e32 v6, s98
	v_mov_b32_e32 v7, s99
	v_cndmask_b32_e32 v2, v0, v24, vcc
	v_mov_b32_e32 v3, 0
	v_cndmask_b32_e32 v4, v4, v6, vcc
	v_cndmask_b32_e32 v5, v5, v7, vcc
	v_lshlrev_b64 v[2:3], 12, v[2:3]
	v_lshl_add_u64 v[2:3], v[4:5], 0, v[2:3]
	v_lshl_add_u64 v[2:3], v[2:3], 0, v[32:33]
	global_load_dwordx4 v[92:95], v[2:3], off
	global_load_dwordx4 v[96:99], v[2:3], off offset:1024
	global_load_dwordx4 v[100:103], v[2:3], off offset:2048
	global_load_dwordx4 v[104:107], v[2:3], off offset:3072
; DI unsigned pk2(float lo, float hi) { const hwf2_t v = {lo, hi}; const hwbf2_t b = __builtin_convertvector(v, hwbf2_t); return __builtin_bit_cast(unsigned, b); }
; DI float wave_sum(float v) { for (int o = 32; o >= 1; o >>= 1) v += __shfl_xor(v, o); return v; }
; DI void ln_pass(CP c, int mode, const float* gam, const float* bet, const float* modsc, const float* modsh, int bid, int nb, bool fin) {
;     ...
;         if (mode != 1) {
;             float s = 0.f;
; #pragma unroll
;             for (int i = 0; i < 4; ++i) s += v[i][0] + v[i][1] + v[i][2] + v[i][3];
;             const float mean = wave_sum(s) * (1.f / 1024.f); float q = 0.f;
; #pragma unroll
;             for (int i = 0; i < 4; ++i) { const f32x4 d = v[i] - mean; q += d[0] * d[0] + d[1] * d[1] + d[2] * d[2] + d[3] * d[3]; }
;             const float rstd = rsqrtf(wave_sum(q) * (1.f / 1024.f) + 1e-5f);
; #pragma unroll
;             for (int i = 0; i < 4; ++i) { const int col = lane * 4 + 256 * i; const f32x4 g = *(const f32x4*)(gam + col), b = *(const f32x4*)(bet + col);
;                 v[i] = (v[i] - mean) * rstd * g + b;
;                 if (fin) *(f32x4*)(c->out + (size_t)r * DM + col) = v[i];
;                 else { u32x2 w; w.x = pk2(v[i][0], v[i][1]); w.y = pk2(v[i][2], v[i][3]); *(u32x2*)(XB + (size_t)r * DM + col) = w; } }
.Lln0_nopf_b:
	s_waitcnt vmcnt(4)
	v_add_f32_e32 v0, v108, v109
	v_add_f32_e32 v0, v0, v110
	v_add_f32_e32 v0, v0, v111
	v_add_f32_e32 v0, v0, v112
	v_add_f32_e32 v0, v0, v113
	v_add_f32_e32 v0, v0, v114
	v_add_f32_e32 v0, v0, v115
	v_add_f32_e32 v0, v0, v116
	v_add_f32_e32 v0, v0, v117
	v_add_f32_e32 v0, v0, v118
	v_add_f32_e32 v0, v0, v119
	v_add_f32_e32 v0, v0, v120
	v_add_f32_e32 v0, v0, v121
	v_add_f32_e32 v0, v0, v122
	v_add_f32_e32 v0, v0, v123
	ds_bpermute_b32 v54, v36, v0
	s_waitcnt lgkmcnt(0)
	v_add_f32_e32 v0, v0, v54
	ds_bpermute_b32 v54, v37, v0
	s_waitcnt lgkmcnt(0)
	v_add_f32_e32 v0, v0, v54
	ds_bpermute_b32 v54, v38, v0
	s_waitcnt lgkmcnt(0)
	v_add_f32_e32 v0, v0, v54
	ds_bpermute_b32 v54, v39, v0
	s_waitcnt lgkmcnt(0)
	v_add_f32_e32 v0, v0, v54
	ds_bpermute_b32 v54, v40, v0
	s_waitcnt lgkmcnt(0)
	v_add_f32_e32 v0, v0, v54
	ds_bpermute_b32 v54, v41, v0
	s_waitcnt lgkmcnt(0)
	v_add_f32_e32 v0, v0, v54
	v_fmac_f32_e32 v108, 0xba800000, v0
	v_fmac_f32_e32 v109, 0xba800000, v0
	v_fmac_f32_e32 v110, 0xba800000, v0
	v_fmac_f32_e32 v111, 0xba800000, v0
	v_fmac_f32_e32 v112, 0xba800000, v0
	v_fmac_f32_e32 v113, 0xba800000, v0
	v_fmac_f32_e32 v114, 0xba800000, v0
	v_fmac_f32_e32 v115, 0xba800000, v0
	v_fmac_f32_e32 v116, 0xba800000, v0
	v_fmac_f32_e32 v117, 0xba800000, v0
	v_fmac_f32_e32 v118, 0xba800000, v0
	v_fmac_f32_e32 v119, 0xba800000, v0
	v_fmac_f32_e32 v120, 0xba800000, v0
	v_fmac_f32_e32 v121, 0xba800000, v0
	v_fmac_f32_e32 v122, 0xba800000, v0
	v_fmac_f32_e32 v123, 0xba800000, v0
	v_mul_f32_e32 v55, v108, v108
	v_fmac_f32_e32 v55, v109, v109
	v_fmac_f32_e32 v55, v110, v110
	v_fmac_f32_e32 v55, v111, v111
	v_fmac_f32_e32 v55, v112, v112
	v_fmac_f32_e32 v55, v113, v113
	v_fmac_f32_e32 v55, v114, v114
	v_fmac_f32_e32 v55, v115, v115
	v_fmac_f32_e32 v55, v116, v116
	v_fmac_f32_e32 v55, v117, v117
	v_fmac_f32_e32 v55, v118, v118
	v_fmac_f32_e32 v55, v119, v119
	v_fmac_f32_e32 v55, v120, v120
	v_fmac_f32_e32 v55, v121, v121
	v_fmac_f32_e32 v55, v122, v122
	v_fmac_f32_e32 v55, v123, v123
	ds_bpermute_b32 v54, v36, v55
	s_waitcnt lgkmcnt(0)
	v_add_f32_e32 v55, v55, v54
	ds_bpermute_b32 v54, v37, v55
	s_waitcnt lgkmcnt(0)
	v_add_f32_e32 v55, v55, v54
	ds_bpermute_b32 v54, v38, v55
	s_waitcnt lgkmcnt(0)
	v_add_f32_e32 v55, v55, v54
	ds_bpermute_b32 v54, v39, v55
	s_waitcnt lgkmcnt(0)
	v_add_f32_e32 v55, v55, v54
	ds_bpermute_b32 v54, v40, v55
	s_waitcnt lgkmcnt(0)
	v_add_f32_e32 v55, v55, v54
	ds_bpermute_b32 v54, v41, v55
	s_waitcnt lgkmcnt(0)
	v_add_f32_e32 v55, v55, v54
	v_fmamk_f32 v55, v55, 0x3a800000, v189
	v_rsq_f32_e32 v55, v55
	s_nop 0
	v_mul_f32_e32 v108, v108, v55
	v_mul_f32_e32 v109, v109, v55
	v_mul_f32_e32 v110, v110, v55
	v_mul_f32_e32 v111, v111, v55
	v_mul_f32_e32 v112, v112, v55
	v_mul_f32_e32 v113, v113, v55
	v_mul_f32_e32 v114, v114, v55
	v_mul_f32_e32 v115, v115, v55
	v_mul_f32_e32 v116, v116, v55
	v_mul_f32_e32 v117, v117, v55
	v_mul_f32_e32 v118, v118, v55
	v_mul_f32_e32 v119, v119, v55
	v_mul_f32_e32 v120, v120, v55
	v_mul_f32_e32 v121, v121, v55
	v_mul_f32_e32 v122, v122, v55
	v_mul_f32_e32 v123, v123, v55
	v_fma_f32 v108, v60, v108, v76
	v_fma_f32 v109, v61, v109, v77
	v_fma_f32 v110, v62, v110, v78
	v_fma_f32 v111, v63, v111, v79
	v_fma_f32 v112, v64, v112, v80
	v_fma_f32 v113, v65, v113, v81
	v_fma_f32 v114, v66, v114, v82
	v_fma_f32 v115, v67, v115, v83
	v_fma_f32 v116, v68, v116, v84
	v_fma_f32 v117, v69, v117, v85
	v_fma_f32 v118, v70, v118, v86
	v_fma_f32 v119, v71, v119, v87
	v_fma_f32 v120, v72, v120, v88
	v_fma_f32 v121, v73, v121, v89
	v_fma_f32 v122, v74, v122, v90
	v_fma_f32 v123, v75, v123, v91
	v_cvt_pk_bf16_f32 v16, v108, v109
	v_cvt_pk_bf16_f32 v17, v110, v111
	global_store_dwordx2 v[30:31], v[16:17], off
	v_cvt_pk_bf16_f32 v18, v112, v113
	v_cvt_pk_bf16_f32 v19, v114, v115
	global_store_dwordx2 v[30:31], v[18:19], off offset:512
	v_cvt_pk_bf16_f32 v20, v116, v117
	v_cvt_pk_bf16_f32 v21, v118, v119
	global_store_dwordx2 v[30:31], v[20:21], off offset:1024
	v_cvt_pk_bf16_f32 v22, v120, v121
	v_cvt_pk_bf16_f32 v23, v122, v123
	global_store_dwordx2 v[30:31], v[22:23], off offset:1536
	v_lshl_add_u64 v[30:31], v[30:31], 0, s[34:35]
	s_andn2_b64 exec, exec, s[12:13]
	s_cbranch_execnz .LBB0_178

; DI void gdn_chunk(CP c, int l, int item, float* sm) {
;     ...
;         const int wv = __builtin_amdgcn_readfirstlane(wave); const int njj = (8 * wv < C) ? wv + 1 : 0;
;         if (njj > 0) {
;             for (int d4 = 0; d4 < 32; ++d4) { const f32x4 ki = *(const f32x4*)(Ks + i * 132 + d4 * 4), qi = *(const f32x4*)(Qs + i * 132 + d4 * 4);
; #pragma unroll
;                 for (int jj = 0; jj < 8; ++jj) if (jj < njj) { const f32x4 kj = *(const f32x4*)(Ks + (t7 + 8 * jj) * 132 + d4 * 4);
;                     kk[jj] += ki[0] * kj[0] + ki[1] * kj[1] + ki[2] * kj[2] + ki[3] * kj[3]; qk[jj] += qi[0] * kj[0] + qi[1] * kj[1] + qi[2] * kj[2] + qi[3] * kj[3]; } }
;         }
.Lkk_ld_p:
.Lkk_loop:
	s_waitcnt lgkmcnt(0)
	s_add_i32 vcc_lo, s0, 16
	v_add_u32_e32 v126, vcc_lo, v0
	ds_read_b128 v[82:85], v126
	ds_read_b128 v[86:89], v126 offset:33792
	v_add_u32_e32 v127, vcc_lo, v15
	ds_read_b128 v[90:93], v127
	s_andn2_b64 vcc, exec, s[6:7]
	s_cbranch_vccnz .Lkk_ld_b
	ds_read_b128 v[94:97], v127 offset:4224
	s_andn2_b64 vcc, exec, s[12:13]
	s_cbranch_vccnz .Lkk_ld_b
	ds_read_b128 v[98:101], v127 offset:8448
	s_andn2_b64 vcc, exec, s[24:25]
	s_cbranch_vccnz .Lkk_ld_b
	ds_read_b128 v[102:105], v127 offset:12672
	s_andn2_b64 vcc, exec, s[26:27]
	s_cbranch_vccnz .Lkk_ld_b
	ds_read_b128 v[106:109], v127 offset:16896
	s_andn2_b64 vcc, exec, s[28:29]
	s_cbranch_vccnz .Lkk_ld_b
	ds_read_b128 v[110:113], v127 offset:21120
	s_andn2_b64 vcc, exec, s[30:31]
	s_cbranch_vccnz .Lkk_ld_b
	ds_read_b128 v[114:117], v127 offset:25344
	s_andn2_b64 vcc, exec, s[34:35]
	s_cbranch_vccnz .Lkk_ld_b
	ds_read_b128 v[118:121], v127 offset:29568
.Lkk_ld_b:
	v_mov_b32_e32 v32, v2
	v_mov_b32_e32 v33, v11
	v_mov_b32_e32 v11, v3
	v_mov_b32_e32 v2, v12
	v_mov_b32_e32 v3, v4
	v_mov_b32_e32 v4, v13
	s_andn2_b64 vcc, exec, s[6:7]
	s_cbranch_vccnz .Lkk_j0_a
	v_pk_mul_f32 v[12:13], v[32:33], v[40:41]
	s_nop 0
	v_pk_fma_f32 v[12:13], v[10:11], v[40:41], v[12:13] op_sel:[0,0,1] op_sel_hi:[1,1,0]
	v_mov_b32_e32 v40, v43
	v_pk_fma_f32 v[12:13], v[2:3], v[42:43], v[12:13] op_sel_hi:[1,0,1]
	s_nop 0
	v_pk_fma_f32 v[12:13], v[4:5], v[40:41], v[12:13] op_sel_hi:[1,0,1]
	s_nop 0
	v_pk_add_f32 v[28:29], v[28:29], v[12:13]
	s_andn2_b64 vcc, exec, s[12:13]
	s_cbranch_vccnz .Lkk_j0_a
	v_pk_mul_f32 v[12:13], v[32:33], v[44:45]
	s_nop 0
	v_pk_fma_f32 v[12:13], v[10:11], v[44:45], v[12:13] op_sel:[0,0,1] op_sel_hi:[1,1,0]
	v_mov_b32_e32 v44, v47
	v_pk_fma_f32 v[12:13], v[2:3], v[46:47], v[12:13] op_sel_hi:[1,0,1]
	s_nop 0
	v_pk_fma_f32 v[12:13], v[4:5], v[44:45], v[12:13] op_sel_hi:[1,0,1]
	s_nop 0
	v_pk_add_f32 v[26:27], v[26:27], v[12:13]
	s_andn2_b64 vcc, exec, s[24:25]
	s_cbranch_vccnz .Lkk_j0_a
	v_pk_mul_f32 v[12:13], v[32:33], v[48:49]
	s_nop 0
	v_pk_fma_f32 v[12:13], v[10:11], v[48:49], v[12:13] op_sel:[0,0,1] op_sel_hi:[1,1,0]
	v_mov_b32_e32 v48, v51
	v_pk_fma_f32 v[12:13], v[2:3], v[50:51], v[12:13] op_sel_hi:[1,0,1]
	s_nop 0
	v_pk_fma_f32 v[12:13], v[4:5], v[48:49], v[12:13] op_sel_hi:[1,0,1]
	s_nop 0
	v_pk_add_f32 v[24:25], v[24:25], v[12:13]
	s_andn2_b64 vcc, exec, s[26:27]
	s_cbranch_vccnz .Lkk_j0_a
	v_pk_mul_f32 v[12:13], v[32:33], v[52:53]
	s_nop 0
	v_pk_fma_f32 v[12:13], v[10:11], v[52:53], v[12:13] op_sel:[0,0,1] op_sel_hi:[1,1,0]
	v_mov_b32_e32 v52, v55
	v_pk_fma_f32 v[12:13], v[2:3], v[54:55], v[12:13] op_sel_hi:[1,0,1]
	s_nop 0
	v_pk_fma_f32 v[12:13], v[4:5], v[52:53], v[12:13] op_sel_hi:[1,0,1]
	s_nop 0
	v_pk_add_f32 v[22:23], v[22:23], v[12:13]
	s_andn2_b64 vcc, exec, s[28:29]
	s_cbranch_vccnz .Lkk_j0_a
	v_pk_mul_f32 v[12:13], v[32:33], v[56:57]
	s_nop 0
	v_pk_fma_f32 v[12:13], v[10:11], v[56:57], v[12:13] op_sel:[0,0,1] op_sel_hi:[1,1,0]
	v_mov_b32_e32 v56, v59
	v_pk_fma_f32 v[12:13], v[2:3], v[58:59], v[12:13] op_sel_hi:[1,0,1]
	s_nop 0
	v_pk_fma_f32 v[12:13], v[4:5], v[56:57], v[12:13] op_sel_hi:[1,0,1]
	s_nop 0
	v_pk_add_f32 v[20:21], v[20:21], v[12:13]
	s_andn2_b64 vcc, exec, s[30:31]
	s_cbranch_vccnz .Lkk_j0_a
	v_pk_mul_f32 v[12:13], v[32:33], v[60:61]
	s_nop 0
	v_pk_fma_f32 v[12:13], v[10:11], v[60:61], v[12:13] op_sel:[0,0,1] op_sel_hi:[1,1,0]
	v_mov_b32_e32 v60, v63
	v_pk_fma_f32 v[12:13], v[2:3], v[62:63], v[12:13] op_sel_hi:[1,0,1]
	s_nop 0
	v_pk_fma_f32 v[12:13], v[4:5], v[60:61], v[12:13] op_sel_hi:[1,0,1]
	s_nop 0
	v_pk_add_f32 v[18:19], v[18:19], v[12:13]
	s_andn2_b64 vcc, exec, s[34:35]
	s_cbranch_vccnz .Lkk_j0_a
	v_pk_mul_f32 v[12:13], v[32:33], v[64:65]
	s_nop 0
	v_pk_fma_f32 v[12:13], v[10:11], v[64:65], v[12:13] op_sel:[0,0,1] op_sel_hi:[1,1,0]
	v_mov_b32_e32 v64, v67
	v_pk_fma_f32 v[12:13], v[2:3], v[66:67], v[12:13] op_sel_hi:[1,0,1]
	s_nop 0
	v_pk_fma_f32 v[12:13], v[4:5], v[64:65], v[12:13] op_sel_hi:[1,0,1]
	s_nop 0
	v_pk_add_f32 v[16:17], v[16:17], v[12:13]
; DI void gdn_chunk(CP c, int l, int item, float* sm) {
;     ...
;         const int wv = __builtin_amdgcn_readfirstlane(wave); const int njj = (8 * wv < C) ? wv + 1 : 0;
;         if (njj > 0) {
;             for (int d4 = 0; d4 < 32; ++d4) { const f32x4 ki = *(const f32x4*)(Ks + i * 132 + d4 * 4), qi = *(const f32x4*)(Qs + i * 132 + d4 * 4);
; #pragma unroll
;                 for (int jj = 0; jj < 8; ++jj) if (jj < njj) { const f32x4 kj = *(const f32x4*)(Ks + (t7 + 8 * jj) * 132 + d4 * 4);
;                     kk[jj] += ki[0] * kj[0] + ki[1] * kj[1] + ki[2] * kj[2] + ki[3] * kj[3]; qk[jj] += qi[0] * kj[0] + qi[1] * kj[1] + qi[2] * kj[2] + qi[3] * kj[3]; } }
;         }
.Lkk_j0_a:
	v_pk_mul_f32 v[12:13], v[32:33], v[6:7]
	s_nop 0
	v_pk_fma_f32 v[6:7], v[10:11], v[6:7], v[12:13] op_sel:[0,0,1] op_sel_hi:[1,1,0]
	s_nop 0
	v_pk_fma_f32 v[2:3], v[2:3], v[8:9], v[6:7] op_sel_hi:[1,0,1]
	v_mov_b32_e32 v6, v9
	v_pk_fma_f32 v[2:3], v[4:5], v[6:7], v[2:3] op_sel_hi:[1,0,1]
	s_nop 0
	v_pk_add_f32 v[30:31], v[30:31], v[2:3]
	s_waitcnt lgkmcnt(0)
	s_add_i32 s0, s0, 32
	s_cmpk_lg_i32 s0, 0x200
	s_cbranch_scc0 .Lkk_last
	v_add_u32_e32 v6, s0, v0
	ds_read_b128 v[2:5], v6
	ds_read_b128 v[10:13], v6 offset:33792
	v_add_u32_e32 v35, s0, v15
	ds_read_b128 v[6:9], v35
	s_andn2_b64 vcc, exec, s[6:7]
	s_cbranch_vccnz .Lkk_ld_a2
	ds_read_b128 v[40:43], v35 offset:4224
	s_andn2_b64 vcc, exec, s[12:13]
	s_cbranch_vccnz .Lkk_ld_a2
	ds_read_b128 v[44:47], v35 offset:8448
	s_andn2_b64 vcc, exec, s[24:25]
	s_cbranch_vccnz .Lkk_ld_a2
	ds_read_b128 v[48:51], v35 offset:12672
	s_andn2_b64 vcc, exec, s[26:27]
	s_cbranch_vccnz .Lkk_ld_a2
	ds_read_b128 v[52:55], v35 offset:16896
	s_andn2_b64 vcc, exec, s[28:29]
	s_cbranch_vccnz .Lkk_ld_a2
	ds_read_b128 v[56:59], v35 offset:21120
	s_andn2_b64 vcc, exec, s[30:31]
	s_cbranch_vccnz .Lkk_ld_a2
	ds_read_b128 v[60:63], v35 offset:25344
	s_andn2_b64 vcc, exec, s[34:35]
	s_cbranch_vccnz .Lkk_ld_a2
	ds_read_b128 v[64:67], v35 offset:29568
.Lkk_ld_a2:
	v_mov_b32_e32 v122, v82
	v_mov_b32_e32 v123, v87
	v_mov_b32_e32 v87, v83
	v_mov_b32_e32 v82, v88
	v_mov_b32_e32 v83, v84
	v_mov_b32_e32 v84, v89
	s_andn2_b64 vcc, exec, s[6:7]
	s_cbranch_vccnz .Lkk_j0_b
	v_pk_mul_f32 v[124:125], v[122:123], v[94:95]
	s_nop 0
	v_pk_fma_f32 v[124:125], v[86:87], v[94:95], v[124:125] op_sel:[0,0,1] op_sel_hi:[1,1,0]
	v_mov_b32_e32 v94, v97
	v_pk_fma_f32 v[124:125], v[82:83], v[96:97], v[124:125] op_sel_hi:[1,0,1]
	s_nop 0
	v_pk_fma_f32 v[124:125], v[84:85], v[94:95], v[124:125] op_sel_hi:[1,0,1]
	s_nop 0
	v_pk_add_f32 v[28:29], v[28:29], v[124:125]
	s_andn2_b64 vcc, exec, s[12:13]
	s_cbranch_vccnz .Lkk_j0_b
	v_pk_mul_f32 v[124:125], v[122:123], v[98:99]
	s_nop 0
	v_pk_fma_f32 v[124:125], v[86:87], v[98:99], v[124:125] op_sel:[0,0,1] op_sel_hi:[1,1,0]
	v_mov_b32_e32 v98, v101
	v_pk_fma_f32 v[124:125], v[82:83], v[100:101], v[124:125] op_sel_hi:[1,0,1]
	s_nop 0
	v_pk_fma_f32 v[124:125], v[84:85], v[98:99], v[124:125] op_sel_hi:[1,0,1]
	s_nop 0
	v_pk_add_f32 v[26:27], v[26:27], v[124:125]
	s_andn2_b64 vcc, exec, s[24:25]
	s_cbranch_vccnz .Lkk_j0_b
	v_pk_mul_f32 v[124:125], v[122:123], v[102:103]
	s_nop 0
	v_pk_fma_f32 v[124:125], v[86:87], v[102:103], v[124:125] op_sel:[0,0,1] op_sel_hi:[1,1,0]
	v_mov_b32_e32 v102, v105
	v_pk_fma_f32 v[124:125], v[82:83], v[104:105], v[124:125] op_sel_hi:[1,0,1]
	s_nop 0
	v_pk_fma_f32 v[124:125], v[84:85], v[102:103], v[124:125] op_sel_hi:[1,0,1]
	s_nop 0
	v_pk_add_f32 v[24:25], v[24:25], v[124:125]
	s_andn2_b64 vcc, exec, s[26:27]
	s_cbranch_vccnz .Lkk_j0_b
	v_pk_mul_f32 v[124:125], v[122:123], v[106:107]
	s_nop 0
	v_pk_fma_f32 v[124:125], v[86:87], v[106:107], v[124:125] op_sel:[0,0,1] op_sel_hi:[1,1,0]
	v_mov_b32_e32 v106, v109
	v_pk_fma_f32 v[124:125], v[82:83], v[108:109], v[124:125] op_sel_hi:[1,0,1]
	s_nop 0
	v_pk_fma_f32 v[124:125], v[84:85], v[106:107], v[124:125] op_sel_hi:[1,0,1]
	s_nop 0
	v_pk_add_f32 v[22:23], v[22:23], v[124:125]
	s_andn2_b64 vcc, exec, s[28:29]
	s_cbranch_vccnz .Lkk_j0_b
	v_pk_mul_f32 v[124:125], v[122:123], v[110:111]
	s_nop 0
	v_pk_fma_f32 v[124:125], v[86:87], v[110:111], v[124:125] op_sel:[0,0,1] op_sel_hi:[1,1,0]
	v_mov_b32_e32 v110, v113
	v_pk_fma_f32 v[124:125], v[82:83], v[112:113], v[124:125] op_sel_hi:[1,0,1]
	s_nop 0
	v_pk_fma_f32 v[124:125], v[84:85], v[110:111], v[124:125] op_sel_hi:[1,0,1]
	s_nop 0
	v_pk_add_f32 v[20:21], v[20:21], v[124:125]
	s_andn2_b64 vcc, exec, s[30:31]
	s_cbranch_vccnz .Lkk_j0_b
	v_pk_mul_f32 v[124:125], v[122:123], v[114:115]
	s_nop 0
	v_pk_fma_f32 v[124:125], v[86:87], v[114:115], v[124:125] op_sel:[0,0,1] op_sel_hi:[1,1,0]
	v_mov_b32_e32 v114, v117
	v_pk_fma_f32 v[124:125], v[82:83], v[116:117], v[124:125] op_sel_hi:[1,0,1]
	s_nop 0
	v_pk_fma_f32 v[124:125], v[84:85], v[114:115], v[124:125] op_sel_hi:[1,0,1]
	s_nop 0
	v_pk_add_f32 v[18:19], v[18:19], v[124:125]
	s_andn2_b64 vcc, exec, s[34:35]
	s_cbranch_vccnz .Lkk_j0_b
	v_pk_mul_f32 v[124:125], v[122:123], v[118:119]
	s_nop 0
	v_pk_fma_f32 v[124:125], v[86:87], v[118:119], v[124:125] op_sel:[0,0,1] op_sel_hi:[1,1,0]
	v_mov_b32_e32 v118, v121
	v_pk_fma_f32 v[124:125], v[82:83], v[120:121], v[124:125] op_sel_hi:[1,0,1]
	s_nop 0
	v_pk_fma_f32 v[124:125], v[84:85], v[118:119], v[124:125] op_sel_hi:[1,0,1]
	s_nop 0
	v_pk_add_f32 v[16:17], v[16:17], v[124:125]
.Lkk_j0_b:
	v_pk_mul_f32 v[124:125], v[122:123], v[90:91]
	s_nop 0
	v_pk_fma_f32 v[90:91], v[86:87], v[90:91], v[124:125] op_sel:[0,0,1] op_sel_hi:[1,1,0]
	s_nop 0
	v_pk_fma_f32 v[82:83], v[82:83], v[92:93], v[90:91] op_sel_hi:[1,0,1]
	v_mov_b32_e32 v90, v93
	v_pk_fma_f32 v[82:83], v[84:85], v[90:91], v[82:83] op_sel_hi:[1,0,1]
	s_nop 0
	v_pk_add_f32 v[30:31], v[30:31], v[82:83]
	s_branch .Lkk_loop

; __global__ void __launch_bounds__(512) fwd_megakernel(Ctx carg) {
;     extern __shared__ __attribute__((aligned(16))) unsigned char smem[];
;     cg::grid_group grid = cg::this_grid();
;     const int bid = blockIdx.x, nb = gridDim.x;
	.amdhsa_kernel _Z14fwd_megakernel3Ctx
		.amdhsa_group_segment_fixed_size 0
		.amdhsa_private_segment_fixed_size 0
		.amdhsa_kernarg_size 576
		.amdhsa_user_sgpr_count 2
		.amdhsa_user_sgpr_dispatch_ptr 0
		.amdhsa_user_sgpr_queue_ptr 0
		.amdhsa_user_sgpr_kernarg_segment_ptr 1
		.amdhsa_user_sgpr_dispatch_id 0
		.amdhsa_user_sgpr_kernarg_preload_length 0
		.amdhsa_user_sgpr_kernarg_preload_offset 0
		.amdhsa_user_sgpr_private_segment_size 0
		.amdhsa_uses_dynamic_stack 0
		.amdhsa_enable_private_segment 0
		.amdhsa_system_sgpr_workgroup_id_x 1
		.amdhsa_system_sgpr_workgroup_id_y 0
		.amdhsa_system_sgpr_workgroup_id_z 0
		.amdhsa_system_sgpr_workgroup_info 0
		.amdhsa_system_vgpr_workitem_id 2
		.amdhsa_next_free_vgpr 256
		.amdhsa_next_free_sgpr 102
		.amdhsa_accum_offset 256
		.amdhsa_reserve_vcc 1
		.amdhsa_float_round_mode_32 0
		.amdhsa_float_round_mode_16_64 0
		.amdhsa_float_denorm_mode_32 3
		.amdhsa_float_denorm_mode_16_64 3
		.amdhsa_dx10_clamp 1
		.amdhsa_ieee_mode 1
		.amdhsa_fp16_overflow 0
		.amdhsa_tg_split 0
		.amdhsa_exception_fp_ieee_invalid_op 0
		.amdhsa_exception_fp_denorm_src 0
		.amdhsa_exception_fp_ieee_div_zero 0
		.amdhsa_exception_fp_ieee_overflow 0
		.amdhsa_exception_fp_ieee_underflow 0
		.amdhsa_exception_fp_ieee_inexact 0
		.amdhsa_exception_int_div_zero 0
	.end_amdhsa_kernel

; __global__ void __launch_bounds__(512) fwd_megakernel(Ctx carg) {
;     extern __shared__ __attribute__((aligned(16))) unsigned char smem[];
;     cg::grid_group grid = cg::this_grid();
;     const int bid = blockIdx.x, nb = gridDim.x;
amdhsa.kernels:
  - .agpr_count:     0
    .args:
      - .offset:         0
        .size:           320
        .value_kind:     by_value
      - .offset:         320
        .size:           4
        .value_kind:     hidden_block_count_x
      - .offset:         324
        .size:           4
        .value_kind:     hidden_block_count_y
      - .offset:         328
        .size:           4
        .value_kind:     hidden_block_count_z
      - .offset:         332
        .size:           2
        .value_kind:     hidden_group_size_x
      - .offset:         334
        .size:           2
        .value_kind:     hidden_group_size_y
      - .offset:         336
        .size:           2
        .value_kind:     hidden_group_size_z
      - .offset:         338
        .size:           2
        .value_kind:     hidden_remainder_x
      - .offset:         340
        .size:           2
        .value_kind:     hidden_remainder_y
      - .offset:         342
        .size:           2
        .value_kind:     hidden_remainder_z
      - .offset:         360
        .size:           8
        .value_kind:     hidden_global_offset_x
      - .offset:         368
        .size:           8
        .value_kind:     hidden_global_offset_y
      - .offset:         376
        .size:           8
        .value_kind:     hidden_global_offset_z
      - .offset:         384
        .size:           2
        .value_kind:     hidden_grid_dims
      - .offset:         408
        .size:           8
        .value_kind:     hidden_multigrid_sync_arg
      - .offset:         440
        .size:           4
        .value_kind:     hidden_dynamic_lds_size
    .group_segment_fixed_size: 0
    .kernarg_segment_align: 8
    .kernarg_segment_size: 576
    .language:       OpenCL C
    .language_version:
      - 2
      - 0
    .max_flat_workgroup_size: 512
    .name:           _Z14fwd_megakernel3Ctx
    .private_segment_fixed_size: 0
    .sgpr_count:     108
    .sgpr_spill_count: 434
    .symbol:         _Z14fwd_megakernel3Ctx.kd
    .uniform_work_group_size: 1
    .uses_dynamic_stack: false
    .vgpr_count:     256
    .vgpr_spill_count: 0
    .wavefront_size: 64
